# k20 + static s_setprio 1 for waves 0-3 from the conv phase through attention (other half of the priority-raise A/B)
# baseline (speedup 1.0000x reference)
; __device__ __forceinline__ void phase_conv(const Params& p, int o, unsigned char* smem, int wave) {
;     const int tid = fresh_tid(wave);
;     c2* buf0 = (c2*)smem;
;     c2* buf1 = (c2*)(smem + 36864);
;     c2* tws = (c2*)(smem + 73728);
;     bf16_t* raw = (bf16_t*)(smem + 106496);
;     const bf16_t* uhy = (const bf16_t*)(p.ws + WS_RB);
;     const bf16_t* z1 = (const bf16_t*)(p.ws + WS_RD);
;     bf16_t* outp = (bf16_t*)(p.ws + (o == 0 ? WS_RD : WS_RE));
;     c2* scr = (c2*)(p.ws + WS_RA + (size_t)blockIdx.x * SCR_PER_BLOCK);
;     const float* normsum = (const float*)(p.ws + WS_NORM);
;     __syncthreads();
;     for (int n = tid; n < 4088; n += NTHR) { int e;
;         if (n < 3584) e = ((n >> 9) + 1) * (n & 511); else if (n < 4032) e = (((n - 3584) >> 6) + 1) * ((n - 3584) & 63) * 8; else e = (((n - 4032) >> 3) + 1) * ((n - 4032) & 7) * 64;
;         float s, c; sincospif((float)e * (1.f / 2048.f), &s, &c); tws[n] = (c2){c, -s}; }
;     __syncthreads();
;     const bool g256 = gridDim.x == 256;
;     const int nrounds = g256 ? 4 : (1024 + gridDim.x - 1) / gridDim.x;
; #pragma unroll 1
;     for (int rd = 0; rd < nrounds; ++rd) {
.LBB0_199:
	s_cmp_ge_u32 s70, 0x100
	s_cbranch_scc1 .Lprio_c
	s_setprio 1
